# stack4: stack3 + first grid sync (after weight conversion) as a flag barrier instead of the cooperative-groups single-counter sync
# speedup vs baseline: 1.0282x; 1.0056x over previous
; template <bool COOP>
; __global__ void __launch_bounds__(512) mk_kernel(Params p, int ph_lo, int ph_hi) {
;     ...
;         if (COOP && ph + 1 < ph_hi) {
;             if (ph == 0) cg::this_grid().sync();
;             else grid_barrier(p.bar, (unsigned)ph);
.LBB0_433:
	s_and_b64 vcc, exec, s[4:5]
	s_cbranch_vccz .LBB0_4
	s_waitcnt vmcnt(0) lgkmcnt(0)
	s_barrier
	v_readfirstlane_b32 s6, v252
	s_nop 3
	s_cmp_lt_u32 s6, 64
	s_cbranch_scc0 .Lfb_others
	buffer_wbl2 sc1
	s_waitcnt vmcnt(0)
	v_readlane_b32 s7, v253, 0
	s_nop 3
	s_lshl_b32 s7, s7, 2
	v_mov_b32_e32 v0, s7
	v_mov_b32_e32 v1, 0x600df1a6
	s_mov_b64 s[8:9], exec
	s_mov_b64 exec, 1
	global_store_dword v0, v1, s[80:81] offset:3072 sc0 sc1
	s_mov_b64 exec, s[8:9]
	s_waitcnt vmcnt(0)
	v_and_b32_e32 v2, 63, v252
	v_lshlrev_b32_e32 v2, 2, v2
	s_mov_b32 s7, 0x100000
.Lfb_poll:
	global_load_dword v3, v2, s[80:81] offset:3072 sc1
	global_load_dword v4, v2, s[80:81] offset:3328 sc1
	global_load_dword v5, v2, s[80:81] offset:3584 sc1
	global_load_dword v6, v2, s[80:81] offset:3840 sc1
	s_waitcnt vmcnt(0)
	v_xor_b32_e32 v3, v3, v1
	v_xor_b32_e32 v4, v4, v1
	v_xor_b32_e32 v5, v5, v1
	v_xor_b32_e32 v6, v6, v1
	v_or3_b32 v3, v3, v4, v5
	v_or_b32_e32 v3, v3, v6
	v_cmp_eq_u32_e32 vcc, 0, v3
	s_nop 3
	s_cmp_eq_u64 vcc, exec
	s_cbranch_scc1 .Lfb_done
	s_sleep 2
	s_sub_u32 s7, s7, 1
	s_cmp_lg_u32 s7, 0
	s_cbranch_scc1 .Lfb_poll

; template <bool COOP>
; __global__ void __launch_bounds__(512) mk_kernel(Params p, int ph_lo, int ph_hi) {
;     ...
;         if (COOP && ph + 1 < ph_hi) {
;             if (ph == 0) cg::this_grid().sync();
;             else grid_barrier(p.bar, (unsigned)ph);
.Lfb_others:
	s_barrier
	s_branch .LBB0_4
.Lfb_cleanup:
	v_readfirstlane_b32 s6, v252
	s_nop 3
	s_cmp_lt_u32 s6, 64
	s_cbranch_scc0 .LBB0_443
	v_readlane_b32 s7, v253, 0
	s_nop 3
	s_lshl_b32 s7, s7, 2
	v_mov_b32_e32 v0, s7
	v_mov_b32_e32 v1, 0
	s_mov_b64 exec, 1
	global_store_dword v0, v1, s[80:81] offset:3072 sc0 sc1
